# v68 + non-temporal hint on mixer-A's streaming loads/stores (run beside the P3b tail GEMM units)
# baseline (speedup 1.0000x reference)
.LBB0_650:
	v_lshl_add_u64 v[44:45], v[66:67], 0, s[20:21]
	v_add_co_u32_e32 v36, vcc, s39, v44
	s_waitcnt vmcnt(3)
	v_pk_mul_f32 v[42:43], v[6:7], v[42:43]
	v_addc_co_u32_e32 v37, vcc, -1, v45, vcc
	v_add_co_u32_e32 v108, vcc, s40, v66
	global_load_dwordx4 v[76:79], v[36:37], off offset:-2048 nt
	s_nop 0
	v_addc_co_u32_e32 v109, vcc, -1, v67, vcc
	v_add_co_u32_e32 v46, vcc, s41, v44
	global_load_dwordx4 v[80:83], v[108:109], off offset:-2048 nt
	s_nop 0
	v_addc_co_u32_e32 v47, vcc, -1, v45, vcc
	v_add_co_u32_e32 v72, vcc, s42, v66
	global_load_dwordx4 v[84:87], v[46:47], off offset:-4096 nt
	s_nop 0
	v_addc_co_u32_e32 v73, vcc, -1, v67, vcc
	global_load_dwordx4 v[88:91], v[72:73], off offset:-4096 nt
	global_load_dwordx4 v[48:51], v[66:67], off offset:-2048 nt
	global_load_dwordx4 v[36:39], v[66:67], off nt
	global_load_dwordx4 v[92:95], v[72:73], off offset:-2048 nt
	global_load_dwordx4 v[96:99], v[72:73], off nt
	global_load_dwordx4 v[100:103], v[46:47], off offset:-2048 nt
	v_add_co_u32_e32 v70, vcc, s44, v66
	v_pk_mul_f32 v[40:41], v[4:5], v[40:41]
	s_nop 0
	v_addc_co_u32_e32 v71, vcc, -1, v67, vcc
	v_add_co_u32_e32 v52, vcc, s43, v44
	s_waitcnt vmcnt(11)
	v_pk_mul_f32 v[34:35], v[2:3], v[34:35]
	v_addc_co_u32_e32 v53, vcc, -1, v45, vcc
	v_add_co_u32_e32 v44, vcc, s45, v44
	v_pk_mul_f32 v[32:33], v[0:1], v[32:33]
	s_nop 0
	v_addc_co_u32_e32 v45, vcc, -1, v45, vcc
	s_waitcnt vmcnt(10)
	v_pk_fma_f32 v[110:111], v[14:15], v[30:31], v[42:43]
	v_pk_fma_f32 v[112:113], v[12:13], v[28:29], v[40:41]
	s_waitcnt vmcnt(9)
	v_pk_fma_f32 v[114:115], v[10:11], v[26:27], v[34:35]
	v_pk_fma_f32 v[116:117], v[8:9], v[24:25], v[32:33]
	global_load_dwordx4 v[104:107], v[46:47], off nt
	global_load_dwordx4 v[60:63], v[52:53], off offset:-2048 nt
	global_load_dwordx4 v[56:59], v[70:71], off offset:-2048 nt
	s_nop 0
	global_load_dwordx4 v[52:55], v[44:45], off offset:-4096 nt
	global_load_dwordx4 v[32:35], v[44:45], off offset:-2048 nt
	global_load_dwordx4 v[40:43], v[66:67], off offset:-4096 nt
	s_nop 0
	global_load_dwordx4 v[44:47], v[44:45], off nt
	s_add_i32 s24, s14, 14
	s_cmp_gt_u32 s24, 61
	s_cselect_b64 s[24:25], -1, 0
	s_and_b64 s[24:25], s[22:23], s[24:25]
	s_andn2_b64 vcc, exec, s[24:25]
	s_waitcnt vmcnt(15)
	v_lshlrev_b32_e32 v118, 16, v76
	v_and_b32_e32 v119, 0xffff0000, v76
	v_lshlrev_b32_e32 v120, 16, v77
	v_and_b32_e32 v121, 0xffff0000, v77
	v_lshlrev_b32_e32 v122, 16, v78
	v_and_b32_e32 v123, 0xffff0000, v78
	v_lshlrev_b32_e32 v124, 16, v79
	v_and_b32_e32 v125, 0xffff0000, v79
	s_waitcnt vmcnt(14)
	v_lshlrev_b32_e32 v76, 16, v80
	v_and_b32_e32 v77, 0xffff0000, v80
	v_lshlrev_b32_e32 v78, 16, v81
	v_and_b32_e32 v79, 0xffff0000, v81
	v_pk_fma_f32 v[112:113], v[20:21], v[118:119], v[112:113]
	v_pk_fma_f32 v[110:111], v[22:23], v[120:121], v[110:111]
	v_lshlrev_b32_e32 v80, 16, v82
	v_and_b32_e32 v81, 0xffff0000, v82
	v_lshlrev_b32_e32 v82, 16, v83
	v_and_b32_e32 v83, 0xffff0000, v83
	v_pk_fma_f32 v[116:117], v[16:17], v[122:123], v[116:117]
	v_pk_fma_f32 v[114:115], v[18:19], v[124:125], v[114:115]
	v_pk_mul_f32 v[78:79], v[110:111], v[78:79]
	v_pk_mul_f32 v[76:77], v[112:113], v[76:77]
	v_pk_mul_f32 v[82:83], v[114:115], v[82:83]
	v_pk_mul_f32 v[80:81], v[116:117], v[80:81]
	v_cvt_pk_bf16_f32 v76, v76, v77
	v_cvt_pk_bf16_f32 v77, v78, v79
	s_waitcnt vmcnt(13)
	v_lshlrev_b32_e32 v128, 16, v86
	v_cvt_pk_bf16_f32 v78, v80, v81
	v_cvt_pk_bf16_f32 v79, v82, v83
	global_store_dwordx4 v[108:109], v[76:79], off offset:-2048 nt
	v_and_b32_e32 v129, 0xffff0000, v86
	s_waitcnt vmcnt(13)
	v_lshlrev_b32_e32 v80, 16, v89
	v_lshlrev_b32_e32 v76, 16, v87
	v_and_b32_e32 v77, 0xffff0000, v87
	v_lshlrev_b32_e32 v78, 16, v88
	v_and_b32_e32 v79, 0xffff0000, v88
	v_and_b32_e32 v81, 0xffff0000, v89
	v_lshlrev_b32_e32 v82, 16, v90
	v_and_b32_e32 v83, 0xffff0000, v90
	v_lshlrev_b32_e32 v86, 16, v91
	v_and_b32_e32 v87, 0xffff0000, v91
	v_pk_mul_f32 v[88:89], v[12:13], v[118:119]
	v_pk_mul_f32 v[90:91], v[14:15], v[120:121]
	v_lshlrev_b32_e32 v126, 16, v84
	v_and_b32_e32 v127, 0xffff0000, v84
	v_lshlrev_b32_e32 v84, 16, v85
	v_and_b32_e32 v85, 0xffff0000, v85
	v_pk_fma_f32 v[30:31], v[6:7], v[30:31], v[90:91]
	v_pk_fma_f32 v[28:29], v[4:5], v[28:29], v[88:89]
	v_pk_fma_f32 v[30:31], v[22:23], v[84:85], v[30:31]
	v_pk_fma_f32 v[28:29], v[20:21], v[126:127], v[28:29]
	v_pk_mul_f32 v[30:31], v[30:31], v[80:81]
	v_pk_mul_f32 v[28:29], v[28:29], v[78:79]
	v_pk_mul_f32 v[78:79], v[8:9], v[122:123]
	v_pk_mul_f32 v[80:81], v[10:11], v[124:125]
	v_pk_fma_f32 v[24:25], v[0:1], v[24:25], v[78:79]
	v_pk_fma_f32 v[26:27], v[2:3], v[26:27], v[80:81]
	v_pk_fma_f32 v[24:25], v[16:17], v[128:129], v[24:25]
	v_pk_fma_f32 v[26:27], v[18:19], v[76:77], v[26:27]
	v_pk_mul_f32 v[90:91], v[14:15], v[84:85]
	v_pk_mul_f32 v[78:79], v[26:27], v[86:87]
	v_pk_mul_f32 v[26:27], v[24:25], v[82:83]
	v_cvt_pk_bf16_f32 v24, v28, v29
	v_cvt_pk_bf16_f32 v25, v30, v31
	s_waitcnt vmcnt(8)
	v_lshlrev_b32_e32 v30, 16, v101
	v_cvt_pk_bf16_f32 v26, v26, v27
	v_cvt_pk_bf16_f32 v27, v78, v79
	v_and_b32_e32 v31, 0xffff0000, v101
	v_pk_mul_f32 v[88:89], v[12:13], v[126:127]
	v_pk_fma_f32 v[90:91], v[6:7], v[120:121], v[90:91]
	global_store_dwordx4 v[72:73], v[24:27], off offset:-4096 nt
	v_lshlrev_b32_e32 v28, 16, v100
	v_and_b32_e32 v29, 0xffff0000, v100
	v_lshlrev_b32_e32 v26, 16, v93
	v_and_b32_e32 v27, 0xffff0000, v93
	v_pk_fma_f32 v[88:89], v[4:5], v[118:119], v[88:89]
	v_pk_fma_f32 v[90:91], v[22:23], v[30:31], v[90:91]
	v_lshlrev_b32_e32 v24, 16, v92
	v_and_b32_e32 v25, 0xffff0000, v92
	v_pk_fma_f32 v[88:89], v[20:21], v[28:29], v[88:89]
	v_pk_mul_f32 v[26:27], v[90:91], v[26:27]
	v_pk_mul_f32 v[90:91], v[10:11], v[76:77]
	v_lshlrev_b32_e32 v80, 16, v103
	v_and_b32_e32 v81, 0xffff0000, v103
	v_pk_mul_f32 v[24:25], v[88:89], v[24:25]
	v_pk_mul_f32 v[88:89], v[8:9], v[128:129]
	v_pk_fma_f32 v[90:91], v[2:3], v[124:125], v[90:91]
	v_lshlrev_b32_e32 v78, 16, v102
	v_and_b32_e32 v79, 0xffff0000, v102
	v_lshlrev_b32_e32 v86, 16, v95
	v_and_b32_e32 v87, 0xffff0000, v95
	v_pk_fma_f32 v[88:89], v[0:1], v[122:123], v[88:89]
	v_pk_fma_f32 v[90:91], v[18:19], v[80:81], v[90:91]
	v_lshlrev_b32_e32 v82, 16, v94
	v_and_b32_e32 v83, 0xffff0000, v94
	v_pk_fma_f32 v[88:89], v[16:17], v[78:79], v[88:89]
	v_pk_mul_f32 v[86:87], v[90:91], v[86:87]
	v_lshlrev_b32_e32 v92, 16, v98
	v_and_b32_e32 v93, 0xffff0000, v98
	v_lshlrev_b32_e32 v94, 16, v99
	v_and_b32_e32 v95, 0xffff0000, v99
	v_pk_mul_f32 v[98:99], v[14:15], v[30:31]
	v_pk_mul_f32 v[82:83], v[88:89], v[82:83]
	v_cvt_pk_bf16_f32 v24, v24, v25
	v_cvt_pk_bf16_f32 v25, v26, v27
	v_pk_fma_f32 v[84:85], v[6:7], v[84:85], v[98:99]
	v_cvt_pk_bf16_f32 v26, v82, v83
	v_cvt_pk_bf16_f32 v27, v86, v87
	s_waitcnt vmcnt(8)
	v_lshlrev_b32_e32 v86, 16, v105
	v_and_b32_e32 v87, 0xffff0000, v105
	global_store_dwordx4 v[72:73], v[24:27], off offset:-2048 nt
	v_pk_fma_f32 v[84:85], v[22:23], v[86:87], v[84:85]
	v_lshlrev_b32_e32 v82, 16, v104
	v_lshlrev_b32_e32 v24, 16, v96
	v_and_b32_e32 v25, 0xffff0000, v96
	v_lshlrev_b32_e32 v26, 16, v97
	v_and_b32_e32 v27, 0xffff0000, v97
	v_pk_mul_f32 v[96:97], v[12:13], v[28:29]
	v_and_b32_e32 v83, 0xffff0000, v104
	v_pk_fma_f32 v[96:97], v[4:5], v[126:127], v[96:97]
	v_pk_mul_f32 v[26:27], v[84:85], v[26:27]
	v_pk_mul_f32 v[84:85], v[8:9], v[78:79]
	v_lshlrev_b32_e32 v88, 16, v106
	v_and_b32_e32 v89, 0xffff0000, v106
	v_pk_fma_f32 v[96:97], v[20:21], v[82:83], v[96:97]
	v_pk_fma_f32 v[84:85], v[0:1], v[128:129], v[84:85]
	v_pk_mul_f32 v[24:25], v[96:97], v[24:25]
	v_pk_mul_f32 v[96:97], v[10:11], v[80:81]
	v_pk_fma_f32 v[84:85], v[16:17], v[88:89], v[84:85]
	v_lshlrev_b32_e32 v90, 16, v107
	v_and_b32_e32 v91, 0xffff0000, v107
	v_pk_fma_f32 v[76:77], v[2:3], v[76:77], v[96:97]
	v_pk_mul_f32 v[84:85], v[84:85], v[92:93]
	v_pk_fma_f32 v[76:77], v[18:19], v[90:91], v[76:77]
	v_cvt_pk_bf16_f32 v24, v24, v25
	v_cvt_pk_bf16_f32 v25, v26, v27
	v_cvt_pk_bf16_f32 v26, v84, v85
	v_pk_mul_f32 v[84:85], v[12:13], v[82:83]
	v_pk_mul_f32 v[92:93], v[14:15], v[86:87]
	v_pk_mul_f32 v[76:77], v[76:77], v[94:95]
	v_pk_fma_f32 v[30:31], v[6:7], v[30:31], v[92:93]
	v_cvt_pk_bf16_f32 v27, v76, v77
	global_store_dwordx4 v[72:73], v[24:27], off nt
	s_waitcnt vmcnt(9)
	v_lshlrev_b32_e32 v72, 16, v60
	v_and_b32_e32 v73, 0xffff0000, v60
	v_lshlrev_b32_e32 v60, 16, v61
	v_and_b32_e32 v61, 0xffff0000, v61
	v_pk_fma_f32 v[28:29], v[4:5], v[28:29], v[84:85]
	s_waitcnt vmcnt(8)
	v_lshlrev_b32_e32 v24, 16, v56
	v_and_b32_e32 v25, 0xffff0000, v56
	v_lshlrev_b32_e32 v26, 16, v57
	v_and_b32_e32 v27, 0xffff0000, v57
	v_pk_fma_f32 v[28:29], v[20:21], v[72:73], v[28:29]
	v_pk_fma_f32 v[30:31], v[22:23], v[60:61], v[30:31]
	v_pk_mul_f32 v[24:25], v[28:29], v[24:25]
	v_pk_mul_f32 v[26:27], v[30:31], v[26:27]
	v_pk_mul_f32 v[28:29], v[8:9], v[88:89]
	v_pk_mul_f32 v[30:31], v[10:11], v[90:91]
	v_lshlrev_b32_e32 v76, 16, v62
	v_and_b32_e32 v77, 0xffff0000, v62
	v_lshlrev_b32_e32 v62, 16, v63
	v_and_b32_e32 v63, 0xffff0000, v63
	v_pk_fma_f32 v[30:31], v[2:3], v[80:81], v[30:31]
	v_pk_fma_f32 v[28:29], v[0:1], v[78:79], v[28:29]
	v_lshlrev_b32_e32 v56, 16, v58
	v_and_b32_e32 v57, 0xffff0000, v58
	v_lshlrev_b32_e32 v58, 16, v59
	v_and_b32_e32 v59, 0xffff0000, v59
	v_pk_fma_f32 v[28:29], v[16:17], v[76:77], v[28:29]
	v_pk_fma_f32 v[30:31], v[18:19], v[62:63], v[30:31]
	v_pk_mul_f32 v[28:29], v[28:29], v[56:57]
	v_pk_mul_f32 v[30:31], v[30:31], v[58:59]
	v_cvt_pk_bf16_f32 v24, v24, v25
	v_cvt_pk_bf16_f32 v25, v26, v27
	v_cvt_pk_bf16_f32 v26, v28, v29
	s_waitcnt vmcnt(5)
	v_lshlrev_b32_e32 v28, 16, v42
	v_cvt_pk_bf16_f32 v27, v30, v31
	global_store_dwordx4 v[70:71], v[24:27], off offset:-2048 nt
	v_and_b32_e32 v29, 0xffff0000, v42
	v_lshlrev_b32_e32 v30, 16, v43
	v_lshlrev_b32_e32 v24, 16, v40
	v_and_b32_e32 v25, 0xffff0000, v40
	v_lshlrev_b32_e32 v26, 16, v41
	v_and_b32_e32 v27, 0xffff0000, v41
	v_and_b32_e32 v31, 0xffff0000, v43
	v_pk_mul_f32 v[40:41], v[12:13], v[72:73]
	v_pk_mul_f32 v[42:43], v[14:15], v[60:61]
	v_lshlrev_b32_e32 v56, 16, v52
	v_and_b32_e32 v57, 0xffff0000, v52
	v_lshlrev_b32_e32 v58, 16, v53
	v_and_b32_e32 v59, 0xffff0000, v53
	v_pk_fma_f32 v[42:43], v[6:7], v[86:87], v[42:43]
	v_pk_fma_f32 v[40:41], v[4:5], v[82:83], v[40:41]
	v_pk_fma_f32 v[42:43], v[22:23], v[58:59], v[42:43]
	v_pk_fma_f32 v[40:41], v[20:21], v[56:57], v[40:41]
	v_pk_mul_f32 v[26:27], v[42:43], v[26:27]
	v_pk_mul_f32 v[24:25], v[40:41], v[24:25]
	v_pk_mul_f32 v[40:41], v[8:9], v[76:77]
	v_pk_mul_f32 v[42:43], v[10:11], v[62:63]
	v_lshlrev_b32_e32 v52, 16, v54
	v_and_b32_e32 v53, 0xffff0000, v54
	v_lshlrev_b32_e32 v54, 16, v55
	v_and_b32_e32 v55, 0xffff0000, v55
	v_pk_fma_f32 v[42:43], v[2:3], v[90:91], v[42:43]
	v_pk_fma_f32 v[40:41], v[0:1], v[88:89], v[40:41]
	v_pk_fma_f32 v[42:43], v[18:19], v[54:55], v[42:43]
	v_pk_fma_f32 v[40:41], v[16:17], v[52:53], v[40:41]
	v_pk_mul_f32 v[30:31], v[42:43], v[30:31]
	v_pk_mul_f32 v[28:29], v[40:41], v[28:29]
	v_cvt_pk_bf16_f32 v24, v24, v25
	v_cvt_pk_bf16_f32 v25, v26, v27
	v_lshlrev_b32_e32 v40, 16, v32
	v_cvt_pk_bf16_f32 v26, v28, v29
	v_cvt_pk_bf16_f32 v27, v30, v31
	global_store_dwordx4 v[66:67], v[24:27], off offset:-4096 nt
	v_lshlrev_b32_e32 v28, 16, v50
	v_and_b32_e32 v29, 0xffff0000, v50
	v_lshlrev_b32_e32 v24, 16, v48
	v_and_b32_e32 v25, 0xffff0000, v48
	v_lshlrev_b32_e32 v26, 16, v49
	v_and_b32_e32 v27, 0xffff0000, v49
	v_lshlrev_b32_e32 v30, 16, v51
	v_and_b32_e32 v31, 0xffff0000, v51
	v_pk_mul_f32 v[48:49], v[12:13], v[56:57]
	v_pk_mul_f32 v[50:51], v[14:15], v[58:59]
	v_and_b32_e32 v41, 0xffff0000, v32
	v_lshlrev_b32_e32 v42, 16, v33
	v_and_b32_e32 v43, 0xffff0000, v33
	v_pk_fma_f32 v[50:51], v[6:7], v[60:61], v[50:51]
	v_pk_fma_f32 v[48:49], v[4:5], v[72:73], v[48:49]
	v_pk_fma_f32 v[50:51], v[22:23], v[42:43], v[50:51]
	v_pk_fma_f32 v[48:49], v[20:21], v[40:41], v[48:49]
	v_pk_mul_f32 v[26:27], v[50:51], v[26:27]
	v_pk_mul_f32 v[24:25], v[48:49], v[24:25]
	v_pk_mul_f32 v[48:49], v[8:9], v[52:53]
	v_pk_mul_f32 v[50:51], v[10:11], v[54:55]
	v_lshlrev_b32_e32 v32, 16, v34
	v_and_b32_e32 v33, 0xffff0000, v34
	v_lshlrev_b32_e32 v34, 16, v35
	v_and_b32_e32 v35, 0xffff0000, v35
	v_pk_fma_f32 v[50:51], v[2:3], v[62:63], v[50:51]
	v_pk_fma_f32 v[48:49], v[0:1], v[76:77], v[48:49]
	v_pk_fma_f32 v[50:51], v[18:19], v[34:35], v[50:51]
	v_pk_fma_f32 v[48:49], v[16:17], v[32:33], v[48:49]
	v_pk_mul_f32 v[30:31], v[50:51], v[30:31]
	v_pk_mul_f32 v[28:29], v[48:49], v[28:29]
	v_cvt_pk_bf16_f32 v24, v24, v25
	v_cvt_pk_bf16_f32 v25, v26, v27
	s_nop 0
	v_cvt_pk_bf16_f32 v26, v28, v29
	v_cvt_pk_bf16_f32 v27, v30, v31
	global_store_dwordx4 v[66:67], v[24:27], off offset:-2048 nt
	s_cbranch_vccnz .LBB0_652
	global_store_dwordx4 v[68:69], v[40:43], off
	global_store_dwordx4 v[68:69], v[32:35], off offset:16
.LBB0_652:
	v_pk_mul_f32 v[48:49], v[14:15], v[42:43]
	v_pk_mul_f32 v[50:51], v[12:13], v[40:41]
	s_waitcnt vmcnt(7)
	v_lshlrev_b32_e32 v28, 16, v44
	v_and_b32_e32 v29, 0xffff0000, v44
	v_lshlrev_b32_e32 v30, 16, v45
	v_and_b32_e32 v31, 0xffff0000, v45
	v_pk_fma_f32 v[48:49], v[6:7], v[58:59], v[48:49]
	v_pk_fma_f32 v[50:51], v[4:5], v[56:57], v[50:51]
	s_add_i32 s24, s14, 15
	v_lshlrev_b32_e32 v44, 16, v36
	v_and_b32_e32 v45, 0xffff0000, v36
	v_lshlrev_b32_e32 v36, 16, v37
	v_and_b32_e32 v37, 0xffff0000, v37
	v_pk_fma_f32 v[48:49], v[22:23], v[30:31], v[48:49]
	v_pk_fma_f32 v[50:51], v[20:21], v[28:29], v[50:51]
	v_pk_mul_f32 v[48:49], v[48:49], v[36:37]
	v_pk_mul_f32 v[36:37], v[50:51], v[44:45]
	v_pk_mul_f32 v[44:45], v[10:11], v[34:35]
	v_pk_mul_f32 v[50:51], v[8:9], v[32:33]
	s_cmp_gt_u32 s24, 61
	v_lshlrev_b32_e32 v24, 16, v46
	v_and_b32_e32 v25, 0xffff0000, v46
	v_lshlrev_b32_e32 v26, 16, v47
	v_and_b32_e32 v27, 0xffff0000, v47
	v_pk_fma_f32 v[44:45], v[2:3], v[54:55], v[44:45]
	v_pk_fma_f32 v[50:51], v[0:1], v[52:53], v[50:51]
	s_cselect_b64 s[24:25], -1, 0
	v_lshlrev_b32_e32 v46, 16, v38
	v_and_b32_e32 v47, 0xffff0000, v38
	v_lshlrev_b32_e32 v38, 16, v39
	v_and_b32_e32 v39, 0xffff0000, v39
	v_pk_fma_f32 v[44:45], v[18:19], v[26:27], v[44:45]
	v_pk_fma_f32 v[50:51], v[16:17], v[24:25], v[50:51]
	s_and_b64 s[24:25], s[22:23], s[24:25]
	v_pk_mul_f32 v[44:45], v[44:45], v[38:39]
	v_pk_mul_f32 v[38:39], v[50:51], v[46:47]
	s_andn2_b64 vcc, exec, s[24:25]
	v_cvt_pk_bf16_f32 v36, v36, v37
	v_cvt_pk_bf16_f32 v37, v48, v49
	v_cvt_pk_bf16_f32 v38, v38, v39
	v_cvt_pk_bf16_f32 v39, v44, v45
	global_store_dwordx4 v[66:67], v[36:39], off nt
	s_cbranch_vccnz .LBB0_649
	s_nop 0
	v_add_co_u32_e32 v36, vcc, 0x1000, v68
	s_nop 1
	v_addc_co_u32_e32 v37, vcc, 0, v69, vcc
	global_store_dwordx4 v[36:37], v[28:31], off
	global_store_dwordx4 v[36:37], v[24:27], off offset:16
	s_branch .LBB0_649
